# grid barrier: generation word spread over 16 cache lines (16 pollers per line instead of 255), last arriver writes all 16
# speedup vs baseline: 1.0013x; 1.0013x over previous
; __device__ __forceinline__ void grid_barrier(unsigned* bar, unsigned& epoch) {
;     ...
;         const unsigned old = __hip_atomic_fetch_add(bar, 1u, __ATOMIC_RELAXED, __HIP_MEMORY_SCOPE_AGENT);
;         if (old + 1u == epoch * gridDim.x) {
;             __hip_atomic_store(bar + 64, epoch, __ATOMIC_RELAXED, __HIP_MEMORY_SCOPE_AGENT);
;         } else {
;             while (__hip_atomic_load(bar + 64, __ATOMIC_RELAXED, __HIP_MEMORY_SCOPE_AGENT) < epoch) __builtin_amdgcn_s_sleep(1);
;         }
.LBB0_276:
	s_or_b64 exec, exec, s[4:5]
	s_waitcnt vmcnt(0)
	v_readfirstlane_b32 s2, v1
	s_nop 1
	v_add3_u32 v0, s2, v0, 1
	v_cmp_ne_u32_e32 vcc, s45, v0
	s_and_saveexec_b64 s[2:3], vcc
	s_xor_b64 s[2:3], exec, s[2:3]
	s_cbranch_execz .LBB0_279
	v_mov_b32_e32 v0, 0
	v_readlane_b32 vcc_lo, v253, 0
	s_and_b32 vcc_lo, vcc_lo, 15
	s_lshl_b32 vcc_lo, vcc_lo, 7
	s_addk_i32 vcc_lo, 0x1400
	v_mov_b32_e32 v0, vcc_lo
	global_load_dword v1, v0, s[30:31] sc1
	s_waitcnt vmcnt(0)
	v_cmp_ne_u32_e32 vcc, 0, v1
	s_cbranch_vccnz .LBB0_279
.LBB0_278:
	s_sleep 1
	global_load_dword v1, v0, s[30:31] sc1
	s_waitcnt vmcnt(0)
	v_cmp_eq_u32_e32 vcc, 0, v1
	s_cbranch_vccnz .LBB0_278
.LBB0_279:
	s_andn2_saveexec_b64 s[2:3], s[2:3]
	s_cbranch_execz .LBB0_281
	v_mov_b32_e32 v0, 0
	v_mov_b32_e32 v1, 1
	v_mov_b32_e32 v0, 0x1400
	global_store_dword v0, v1, s[30:31] sc1
	global_store_dword v0, v1, s[30:31] offset:128 sc1
	global_store_dword v0, v1, s[30:31] offset:256 sc1
	global_store_dword v0, v1, s[30:31] offset:384 sc1
	global_store_dword v0, v1, s[30:31] offset:512 sc1
	global_store_dword v0, v1, s[30:31] offset:640 sc1
	global_store_dword v0, v1, s[30:31] offset:768 sc1
	global_store_dword v0, v1, s[30:31] offset:896 sc1
	global_store_dword v0, v1, s[30:31] offset:1024 sc1
	global_store_dword v0, v1, s[30:31] offset:1152 sc1
	global_store_dword v0, v1, s[30:31] offset:1280 sc1
	global_store_dword v0, v1, s[30:31] offset:1408 sc1
	global_store_dword v0, v1, s[30:31] offset:1536 sc1
	global_store_dword v0, v1, s[30:31] offset:1664 sc1
	global_store_dword v0, v1, s[30:31] offset:1792 sc1
	global_store_dword v0, v1, s[30:31] offset:1920 sc1

; __device__ __forceinline__ void grid_barrier(unsigned* bar, unsigned& epoch) {
;     ...
;         const unsigned old = __hip_atomic_fetch_add(bar, 1u, __ATOMIC_RELAXED, __HIP_MEMORY_SCOPE_AGENT);
;         if (old + 1u == epoch * gridDim.x) {
;             __hip_atomic_store(bar + 64, epoch, __ATOMIC_RELAXED, __HIP_MEMORY_SCOPE_AGENT);
;         } else {
;             while (__hip_atomic_load(bar + 64, __ATOMIC_RELAXED, __HIP_MEMORY_SCOPE_AGENT) < epoch) __builtin_amdgcn_s_sleep(1);
;         }
.LBB0_292:
	s_or_b64 exec, exec, s[4:5]
	s_waitcnt vmcnt(0)
	v_readfirstlane_b32 s2, v1
	s_nop 1
	v_add3_u32 v0, s2, v0, 1
	s_lshl_b32 s2, s45, 1
	v_cmp_ne_u32_e32 vcc, s2, v0
	s_and_saveexec_b64 s[2:3], vcc
	s_xor_b64 s[2:3], exec, s[2:3]
	s_cbranch_execz .LBB0_295
	v_mov_b32_e32 v0, 0
	v_readlane_b32 vcc_lo, v253, 0
	s_and_b32 vcc_lo, vcc_lo, 15
	s_lshl_b32 vcc_lo, vcc_lo, 7
	s_addk_i32 vcc_lo, 0x1400
	v_mov_b32_e32 v0, vcc_lo
	global_load_dword v1, v0, s[30:31] sc1
	s_waitcnt vmcnt(0)
	v_cmp_lt_u32_e32 vcc, 1, v1
	s_cbranch_vccnz .LBB0_295
.LBB0_294:
	s_sleep 1
	global_load_dword v1, v0, s[30:31] sc1
	s_waitcnt vmcnt(0)
	v_cmp_gt_u32_e32 vcc, 2, v1
	s_cbranch_vccnz .LBB0_294
.LBB0_295:
	s_andn2_saveexec_b64 s[2:3], s[2:3]
	s_cbranch_execz .LBB0_297
	v_mov_b32_e32 v0, 0
	v_mov_b32_e32 v1, 2
	v_mov_b32_e32 v0, 0x1400
	global_store_dword v0, v1, s[30:31] sc1
	global_store_dword v0, v1, s[30:31] offset:128 sc1
	global_store_dword v0, v1, s[30:31] offset:256 sc1
	global_store_dword v0, v1, s[30:31] offset:384 sc1
	global_store_dword v0, v1, s[30:31] offset:512 sc1
	global_store_dword v0, v1, s[30:31] offset:640 sc1
	global_store_dword v0, v1, s[30:31] offset:768 sc1
	global_store_dword v0, v1, s[30:31] offset:896 sc1
	global_store_dword v0, v1, s[30:31] offset:1024 sc1
	global_store_dword v0, v1, s[30:31] offset:1152 sc1
	global_store_dword v0, v1, s[30:31] offset:1280 sc1
	global_store_dword v0, v1, s[30:31] offset:1408 sc1
	global_store_dword v0, v1, s[30:31] offset:1536 sc1
	global_store_dword v0, v1, s[30:31] offset:1664 sc1
	global_store_dword v0, v1, s[30:31] offset:1792 sc1
	global_store_dword v0, v1, s[30:31] offset:1920 sc1

; __device__ __forceinline__ void grid_barrier(unsigned* bar, unsigned& epoch) {
;     ...
;         const unsigned old = __hip_atomic_fetch_add(bar, 1u, __ATOMIC_RELAXED, __HIP_MEMORY_SCOPE_AGENT);
;         if (old + 1u == epoch * gridDim.x) {
;             __hip_atomic_store(bar + 64, epoch, __ATOMIC_RELAXED, __HIP_MEMORY_SCOPE_AGENT);
;         } else {
;             while (__hip_atomic_load(bar + 64, __ATOMIC_RELAXED, __HIP_MEMORY_SCOPE_AGENT) < epoch) __builtin_amdgcn_s_sleep(1);
;         }
.LBB0_368:
	s_or_b64 exec, exec, s[6:7]
	s_add_i32 s6, s82, 1
	s_waitcnt vmcnt(0)
	v_readfirstlane_b32 s4, v1
	s_nop 1
	v_add3_u32 v0, s4, v0, 1
	s_mul_i32 s4, s6, s45
	v_cmp_ne_u32_e32 vcc, s4, v0
	s_and_saveexec_b64 s[4:5], vcc
	v_readlane_b32 s22, v254, 35
	s_xor_b64 s[4:5], exec, s[4:5]
	v_readlane_b32 s23, v254, 36
	s_cbranch_execz .LBB0_371
	s_nop 3
	v_readlane_b32 vcc_lo, v253, 0
	s_and_b32 vcc_lo, vcc_lo, 15
	s_lshl_b32 vcc_lo, vcc_lo, 7
	s_addk_i32 vcc_lo, 0x1400
	v_mov_b32_e32 v1, vcc_lo
	global_load_dword v0, v1, s[22:23] sc1
	s_waitcnt vmcnt(0)
	v_cmp_le_u32_e32 vcc, s6, v0
	s_cbranch_vccnz .LBB0_371
.LBB0_370:
	s_sleep 1
	global_load_dword v0, v1, s[22:23] sc1
	s_waitcnt vmcnt(0)
	v_cmp_gt_u32_e32 vcc, s6, v0
	s_cbranch_vccnz .LBB0_370
.LBB0_371:
	s_andn2_saveexec_b64 s[4:5], s[4:5]
	s_cbranch_execz .LBB0_373
	v_mov_b32_e32 v0, s6
	v_readlane_b32 s6, v254, 35
	v_readlane_b32 s7, v254, 36
	s_nop 4
	v_mov_b32_e32 v1, 0x1400
	global_store_dword v1, v0, s[6:7] sc1
	global_store_dword v1, v0, s[6:7] offset:128 sc1
	global_store_dword v1, v0, s[6:7] offset:256 sc1
	global_store_dword v1, v0, s[6:7] offset:384 sc1
	global_store_dword v1, v0, s[6:7] offset:512 sc1
	global_store_dword v1, v0, s[6:7] offset:640 sc1
	global_store_dword v1, v0, s[6:7] offset:768 sc1
	global_store_dword v1, v0, s[6:7] offset:896 sc1
	global_store_dword v1, v0, s[6:7] offset:1024 sc1
	global_store_dword v1, v0, s[6:7] offset:1152 sc1
	global_store_dword v1, v0, s[6:7] offset:1280 sc1
	global_store_dword v1, v0, s[6:7] offset:1408 sc1
	global_store_dword v1, v0, s[6:7] offset:1536 sc1
	global_store_dword v1, v0, s[6:7] offset:1664 sc1
	global_store_dword v1, v0, s[6:7] offset:1792 sc1
	global_store_dword v1, v0, s[6:7] offset:1920 sc1

; __device__ __forceinline__ void grid_barrier(unsigned* bar, unsigned& epoch) {
;     ...
;         const unsigned old = __hip_atomic_fetch_add(bar, 1u, __ATOMIC_RELAXED, __HIP_MEMORY_SCOPE_AGENT);
;         if (old + 1u == epoch * gridDim.x) {
;             __hip_atomic_store(bar + 64, epoch, __ATOMIC_RELAXED, __HIP_MEMORY_SCOPE_AGENT);
;         } else {
;             while (__hip_atomic_load(bar + 64, __ATOMIC_RELAXED, __HIP_MEMORY_SCOPE_AGENT) < epoch) __builtin_amdgcn_s_sleep(1);
;         }
.LBB0_389:
	s_or_b64 exec, exec, s[6:7]
	s_add_i32 s6, s82, 2
	s_waitcnt vmcnt(0)
	v_readfirstlane_b32 s4, v1
	s_nop 1
	v_add3_u32 v0, s4, v0, 1
	s_mul_i32 s4, s6, s45
	v_cmp_ne_u32_e32 vcc, s4, v0
	s_and_saveexec_b64 s[4:5], vcc
	v_readlane_b32 s22, v254, 35
	s_xor_b64 s[4:5], exec, s[4:5]
	v_readlane_b32 s23, v254, 36
	s_cbranch_execz .LBB0_392
	s_nop 3
	v_readlane_b32 vcc_lo, v253, 0
	s_and_b32 vcc_lo, vcc_lo, 15
	s_lshl_b32 vcc_lo, vcc_lo, 7
	s_addk_i32 vcc_lo, 0x1400
	v_mov_b32_e32 v1, vcc_lo
	global_load_dword v0, v1, s[22:23] sc1
	s_waitcnt vmcnt(0)
	v_cmp_le_u32_e32 vcc, s6, v0
	s_cbranch_vccnz .LBB0_392

; __device__ __forceinline__ void grid_barrier(unsigned* bar, unsigned& epoch) {
;     ...
;         const unsigned old = __hip_atomic_fetch_add(bar, 1u, __ATOMIC_RELAXED, __HIP_MEMORY_SCOPE_AGENT);
;         if (old + 1u == epoch * gridDim.x) {
;             __hip_atomic_store(bar + 64, epoch, __ATOMIC_RELAXED, __HIP_MEMORY_SCOPE_AGENT);
;         } else {
;             while (__hip_atomic_load(bar + 64, __ATOMIC_RELAXED, __HIP_MEMORY_SCOPE_AGENT) < epoch) __builtin_amdgcn_s_sleep(1);
;         }
.LBB0_507:
	s_or_b64 exec, exec, s[6:7]
	s_add_i32 s6, s82, 3
	s_waitcnt vmcnt(0)
	v_readfirstlane_b32 s4, v1
	s_nop 1
	v_add3_u32 v0, s4, v0, 1
	s_mul_i32 s4, s6, s45
	v_cmp_ne_u32_e32 vcc, s4, v0
	s_and_saveexec_b64 s[4:5], vcc
	v_readlane_b32 s22, v254, 35
	s_xor_b64 s[4:5], exec, s[4:5]
	v_readlane_b32 s23, v254, 36
	s_cbranch_execz .LBB0_510
	s_nop 3
	v_readlane_b32 vcc_lo, v253, 0
	s_and_b32 vcc_lo, vcc_lo, 15
	s_lshl_b32 vcc_lo, vcc_lo, 7
	s_addk_i32 vcc_lo, 0x1400
	v_mov_b32_e32 v1, vcc_lo
	global_load_dword v0, v1, s[22:23] sc1
	s_waitcnt vmcnt(0)
	v_cmp_le_u32_e32 vcc, s6, v0
	s_cbranch_vccnz .LBB0_510

; __device__ __forceinline__ void grid_barrier(unsigned* bar, unsigned& epoch) {
;     ...
;         const unsigned old = __hip_atomic_fetch_add(bar, 1u, __ATOMIC_RELAXED, __HIP_MEMORY_SCOPE_AGENT);
;         if (old + 1u == epoch * gridDim.x) {
;             __hip_atomic_store(bar + 64, epoch, __ATOMIC_RELAXED, __HIP_MEMORY_SCOPE_AGENT);
;         } else {
;             while (__hip_atomic_load(bar + 64, __ATOMIC_RELAXED, __HIP_MEMORY_SCOPE_AGENT) < epoch) __builtin_amdgcn_s_sleep(1);
;         }
.LBB0_639:
	s_or_b64 exec, exec, s[6:7]
	s_add_i32 s6, s82, 4
	s_waitcnt vmcnt(0)
	v_readfirstlane_b32 s4, v1
	s_nop 1
	v_add3_u32 v0, s4, v0, 1
	s_mul_i32 s4, s6, s45
	v_cmp_ne_u32_e32 vcc, s4, v0
	s_and_saveexec_b64 s[4:5], vcc
	v_readlane_b32 s22, v254, 35
	s_xor_b64 s[4:5], exec, s[4:5]
	v_readlane_b32 s23, v254, 36
	s_cbranch_execz .LBB0_642
	s_nop 3
	v_readlane_b32 vcc_lo, v253, 0
	s_and_b32 vcc_lo, vcc_lo, 15
	s_lshl_b32 vcc_lo, vcc_lo, 7
	s_addk_i32 vcc_lo, 0x1400
	v_mov_b32_e32 v1, vcc_lo
	global_load_dword v0, v1, s[22:23] sc1
	s_waitcnt vmcnt(0)
	v_cmp_le_u32_e32 vcc, s6, v0
	s_cbranch_vccnz .LBB0_642

; __device__ __forceinline__ void grid_barrier(unsigned* bar, unsigned& epoch) {
;     ...
;         const unsigned old = __hip_atomic_fetch_add(bar, 1u, __ATOMIC_RELAXED, __HIP_MEMORY_SCOPE_AGENT);
;         if (old + 1u == epoch * gridDim.x) {
;             __hip_atomic_store(bar + 64, epoch, __ATOMIC_RELAXED, __HIP_MEMORY_SCOPE_AGENT);
;         } else {
;             while (__hip_atomic_load(bar + 64, __ATOMIC_RELAXED, __HIP_MEMORY_SCOPE_AGENT) < epoch) __builtin_amdgcn_s_sleep(1);
;         }
.LBB0_671:
	s_or_b64 exec, exec, s[6:7]
	s_add_i32 s6, s82, 5
	s_waitcnt vmcnt(0)
	v_readfirstlane_b32 s4, v1
	s_nop 1
	v_add3_u32 v0, s4, v0, 1
	s_mul_i32 s4, s6, s45
	v_cmp_ne_u32_e32 vcc, s4, v0
	s_and_saveexec_b64 s[4:5], vcc
	v_readlane_b32 s42, v254, 35
	s_xor_b64 s[4:5], exec, s[4:5]
	v_readlane_b32 s43, v254, 36
	s_cbranch_execz .LBB0_674
	s_nop 3
	v_readlane_b32 vcc_lo, v253, 0
	s_and_b32 vcc_lo, vcc_lo, 15
	s_lshl_b32 vcc_lo, vcc_lo, 7
	s_addk_i32 vcc_lo, 0x1400
	v_mov_b32_e32 v1, vcc_lo
	global_load_dword v0, v1, s[42:43] sc1
	s_waitcnt vmcnt(0)
	v_cmp_le_u32_e32 vcc, s6, v0
	s_cbranch_vccnz .LBB0_674
.LBB0_673:
	s_sleep 1
	global_load_dword v0, v1, s[42:43] sc1
	s_waitcnt vmcnt(0)
	v_cmp_gt_u32_e32 vcc, s6, v0
	s_cbranch_vccnz .LBB0_673

; __device__ __forceinline__ void grid_barrier(unsigned* bar, unsigned& epoch) {
;     ...
;         const unsigned old = __hip_atomic_fetch_add(bar, 1u, __ATOMIC_RELAXED, __HIP_MEMORY_SCOPE_AGENT);
;         if (old + 1u == epoch * gridDim.x) {
;             __hip_atomic_store(bar + 64, epoch, __ATOMIC_RELAXED, __HIP_MEMORY_SCOPE_AGENT);
;         } else {
;             while (__hip_atomic_load(bar + 64, __ATOMIC_RELAXED, __HIP_MEMORY_SCOPE_AGENT) < epoch) __builtin_amdgcn_s_sleep(1);
;         }
.LBB0_725:
	s_or_b64 exec, exec, s[6:7]
	s_add_i32 s6, s82, 6
	s_waitcnt vmcnt(0)
	v_readfirstlane_b32 s4, v1
	s_nop 1
	v_add3_u32 v0, s4, v0, 1
	s_mul_i32 s4, s6, s45
	v_cmp_ne_u32_e32 vcc, s4, v0
	s_and_saveexec_b64 s[4:5], vcc
	v_readlane_b32 s42, v254, 35
	s_xor_b64 s[4:5], exec, s[4:5]
	v_readlane_b32 s43, v254, 36
	s_cbranch_execz .LBB0_728
	s_nop 3
	v_readlane_b32 vcc_lo, v253, 0
	s_and_b32 vcc_lo, vcc_lo, 15
	s_lshl_b32 vcc_lo, vcc_lo, 7
	s_addk_i32 vcc_lo, 0x1400
	v_mov_b32_e32 v1, vcc_lo
	global_load_dword v0, v1, s[42:43] sc1
	s_waitcnt vmcnt(0)
	v_cmp_le_u32_e32 vcc, s6, v0
	s_cbranch_vccnz .LBB0_728

; __device__ __forceinline__ void grid_barrier(unsigned* bar, unsigned& epoch) {
;     ...
;         const unsigned old = __hip_atomic_fetch_add(bar, 1u, __ATOMIC_RELAXED, __HIP_MEMORY_SCOPE_AGENT);
;         if (old + 1u == epoch * gridDim.x) {
;             __hip_atomic_store(bar + 64, epoch, __ATOMIC_RELAXED, __HIP_MEMORY_SCOPE_AGENT);
;         } else {
;             while (__hip_atomic_load(bar + 64, __ATOMIC_RELAXED, __HIP_MEMORY_SCOPE_AGENT) < epoch) __builtin_amdgcn_s_sleep(1);
;         }
.LBB0_993:
	s_or_b64 exec, exec, s[6:7]
	s_add_i32 s6, s82, 7
	s_waitcnt vmcnt(0)
	v_readfirstlane_b32 s4, v1
	s_nop 1
	v_add3_u32 v0, s4, v0, 1
	s_mul_i32 s4, s6, s45
	v_cmp_ne_u32_e32 vcc, s4, v0
	s_and_saveexec_b64 s[4:5], vcc
	v_readlane_b32 s42, v254, 35
	s_xor_b64 s[4:5], exec, s[4:5]
	v_readlane_b32 s43, v254, 36
	s_cbranch_execz .LBB0_996
	s_nop 3
	v_readlane_b32 vcc_lo, v253, 0
	s_and_b32 vcc_lo, vcc_lo, 15
	s_lshl_b32 vcc_lo, vcc_lo, 7
	s_addk_i32 vcc_lo, 0x1400
	v_mov_b32_e32 v1, vcc_lo
	global_load_dword v0, v1, s[42:43] sc1
	s_waitcnt vmcnt(0)
	v_cmp_le_u32_e32 vcc, s6, v0
	s_cbranch_vccnz .LBB0_996

; __device__ __forceinline__ void grid_barrier(unsigned* bar, unsigned& epoch) {
;     ...
;         const unsigned old = __hip_atomic_fetch_add(bar, 1u, __ATOMIC_RELAXED, __HIP_MEMORY_SCOPE_AGENT);
;         if (old + 1u == epoch * gridDim.x) {
;             __hip_atomic_store(bar + 64, epoch, __ATOMIC_RELAXED, __HIP_MEMORY_SCOPE_AGENT);
;         } else {
;             while (__hip_atomic_load(bar + 64, __ATOMIC_RELAXED, __HIP_MEMORY_SCOPE_AGENT) < epoch) __builtin_amdgcn_s_sleep(1);
;         }
.LBB0_1007:
	s_or_b64 exec, exec, s[48:49]
	s_add_i32 s2, s82, 8
	s_waitcnt vmcnt(0)
	v_readfirstlane_b32 s3, v1
	s_nop 1
	v_add3_u32 v0, s3, v0, 1
	s_mul_i32 s3, s2, s45
	v_cmp_ne_u32_e32 vcc, s3, v0
	s_and_saveexec_b64 s[38:39], vcc
	s_xor_b64 s[46:47], exec, s[38:39]
	v_readlane_b32 s38, v254, 35
	v_readlane_b32 s39, v254, 36
	s_cbranch_execz .LBB0_1010
	s_nop 3
	v_readlane_b32 vcc_lo, v253, 0
	s_and_b32 vcc_lo, vcc_lo, 15
	s_lshl_b32 vcc_lo, vcc_lo, 7
	s_addk_i32 vcc_lo, 0x1400
	v_mov_b32_e32 v1, vcc_lo
	global_load_dword v0, v1, s[38:39] sc1
	s_waitcnt vmcnt(0)
	v_cmp_le_u32_e32 vcc, s2, v0
	s_cbranch_vccnz .LBB0_1010
.LBB0_1009:
	s_sleep 1
	global_load_dword v0, v1, s[38:39] sc1
	s_waitcnt vmcnt(0)
	v_cmp_gt_u32_e32 vcc, s2, v0
	s_cbranch_vccnz .LBB0_1009
.LBB0_1010:
	s_andn2_saveexec_b64 s[46:47], s[46:47]
	s_cbranch_execz .LBB0_1012
	v_mov_b32_e32 v0, s2
	v_readlane_b32 s2, v254, 35
	v_readlane_b32 s3, v254, 36
	s_nop 4
	v_mov_b32_e32 v1, 0x1400
	global_store_dword v1, v0, s[2:3] sc1
	global_store_dword v1, v0, s[2:3] offset:128 sc1
	global_store_dword v1, v0, s[2:3] offset:256 sc1
	global_store_dword v1, v0, s[2:3] offset:384 sc1
	global_store_dword v1, v0, s[2:3] offset:512 sc1
	global_store_dword v1, v0, s[2:3] offset:640 sc1
	global_store_dword v1, v0, s[2:3] offset:768 sc1
	global_store_dword v1, v0, s[2:3] offset:896 sc1
	global_store_dword v1, v0, s[2:3] offset:1024 sc1
	global_store_dword v1, v0, s[2:3] offset:1152 sc1
	global_store_dword v1, v0, s[2:3] offset:1280 sc1
	global_store_dword v1, v0, s[2:3] offset:1408 sc1
	global_store_dword v1, v0, s[2:3] offset:1536 sc1
	global_store_dword v1, v0, s[2:3] offset:1664 sc1
	global_store_dword v1, v0, s[2:3] offset:1792 sc1
	global_store_dword v1, v0, s[2:3] offset:1920 sc1

; __device__ __forceinline__ void grid_barrier(unsigned* bar, unsigned& epoch) {
;     ...
;         const unsigned old = __hip_atomic_fetch_add(bar, 1u, __ATOMIC_RELAXED, __HIP_MEMORY_SCOPE_AGENT);
;         if (old + 1u == epoch * gridDim.x) {
;             __hip_atomic_store(bar + 64, epoch, __ATOMIC_RELAXED, __HIP_MEMORY_SCOPE_AGENT);
;         } else {
;             while (__hip_atomic_load(bar + 64, __ATOMIC_RELAXED, __HIP_MEMORY_SCOPE_AGENT) < epoch) __builtin_amdgcn_s_sleep(1);
;         }
.LBB0_1048:
	s_or_b64 exec, exec, s[48:49]
	s_add_i32 s2, s82, 9
	s_waitcnt vmcnt(0)
	v_readfirstlane_b32 s3, v1
	s_nop 1
	v_add3_u32 v0, s3, v0, 1
	s_mul_i32 s3, s2, s45
	v_cmp_ne_u32_e32 vcc, s3, v0
	s_and_saveexec_b64 s[38:39], vcc
	s_xor_b64 s[46:47], exec, s[38:39]
	v_readlane_b32 s38, v254, 35
	v_readlane_b32 s39, v254, 36
	s_cbranch_execz .LBB0_1051
	s_nop 3
	v_readlane_b32 vcc_lo, v253, 0
	s_and_b32 vcc_lo, vcc_lo, 15
	s_lshl_b32 vcc_lo, vcc_lo, 7
	s_addk_i32 vcc_lo, 0x1400
	v_mov_b32_e32 v1, vcc_lo
	global_load_dword v0, v1, s[38:39] sc1
	s_waitcnt vmcnt(0)
	v_cmp_le_u32_e32 vcc, s2, v0
	s_cbranch_vccnz .LBB0_1051

; __device__ __forceinline__ void grid_barrier(unsigned* bar, unsigned& epoch) {
;     ...
;         const unsigned old = __hip_atomic_fetch_add(bar, 1u, __ATOMIC_RELAXED, __HIP_MEMORY_SCOPE_AGENT);
;         if (old + 1u == epoch * gridDim.x) {
;             __hip_atomic_store(bar + 64, epoch, __ATOMIC_RELAXED, __HIP_MEMORY_SCOPE_AGENT);
;         } else {
;             while (__hip_atomic_load(bar + 64, __ATOMIC_RELAXED, __HIP_MEMORY_SCOPE_AGENT) < epoch) __builtin_amdgcn_s_sleep(1);
;         }
.LBB0_1116:
	s_or_b64 exec, exec, s[42:43]
	s_waitcnt vmcnt(0)
	v_readfirstlane_b32 s2, v1
	s_nop 1
	v_add3_u32 v0, s2, v0, 1
	s_mul_i32 s2, s18, s45
	v_cmp_ne_u32_e32 vcc, s2, v0
	s_and_saveexec_b64 s[2:3], vcc
	s_xor_b64 s[6:7], exec, s[2:3]
	v_readlane_b32 s2, v254, 35
	v_readlane_b32 s3, v254, 36
	s_cbranch_execz .LBB0_1119
	s_nop 3
	v_readlane_b32 vcc_lo, v253, 0
	s_and_b32 vcc_lo, vcc_lo, 15
	s_lshl_b32 vcc_lo, vcc_lo, 7
	s_addk_i32 vcc_lo, 0x1400
	v_mov_b32_e32 v1, vcc_lo
	global_load_dword v0, v1, s[2:3] sc1
	s_waitcnt vmcnt(0)
	v_cmp_le_u32_e32 vcc, s18, v0
	s_cbranch_vccnz .LBB0_1119
.LBB0_1118:
	s_sleep 1
	global_load_dword v0, v1, s[2:3] sc1
	s_waitcnt vmcnt(0)
	v_cmp_gt_u32_e32 vcc, s18, v0
	s_cbranch_vccnz .LBB0_1118
.LBB0_1119:
	s_andn2_saveexec_b64 s[6:7], s[6:7]
	s_cbranch_execz .LBB0_1121
	v_readlane_b32 s2, v254, 35
	v_mov_b32_e32 v0, s18
	v_readlane_b32 s3, v254, 36
	s_nop 4
	v_mov_b32_e32 v1, 0x1400
	global_store_dword v1, v0, s[2:3] sc1
	global_store_dword v1, v0, s[2:3] offset:128 sc1
	global_store_dword v1, v0, s[2:3] offset:256 sc1
	global_store_dword v1, v0, s[2:3] offset:384 sc1
	global_store_dword v1, v0, s[2:3] offset:512 sc1
	global_store_dword v1, v0, s[2:3] offset:640 sc1
	global_store_dword v1, v0, s[2:3] offset:768 sc1
	global_store_dword v1, v0, s[2:3] offset:896 sc1
	global_store_dword v1, v0, s[2:3] offset:1024 sc1
	global_store_dword v1, v0, s[2:3] offset:1152 sc1
	global_store_dword v1, v0, s[2:3] offset:1280 sc1
	global_store_dword v1, v0, s[2:3] offset:1408 sc1
	global_store_dword v1, v0, s[2:3] offset:1536 sc1
	global_store_dword v1, v0, s[2:3] offset:1664 sc1
	global_store_dword v1, v0, s[2:3] offset:1792 sc1
	global_store_dword v1, v0, s[2:3] offset:1920 sc1

; __device__ __forceinline__ void grid_barrier(unsigned* bar, unsigned& epoch) {
;     ...
;         const unsigned old = __hip_atomic_fetch_add(bar, 1u, __ATOMIC_RELAXED, __HIP_MEMORY_SCOPE_AGENT);
;         if (old + 1u == epoch * gridDim.x) {
;             __hip_atomic_store(bar + 64, epoch, __ATOMIC_RELAXED, __HIP_MEMORY_SCOPE_AGENT);
;         } else {
;             while (__hip_atomic_load(bar + 64, __ATOMIC_RELAXED, __HIP_MEMORY_SCOPE_AGENT) < epoch) __builtin_amdgcn_s_sleep(1);
;         }
.LBB0_1402:
	s_or_b64 exec, exec, s[6:7]
	s_waitcnt vmcnt(0)
	v_readfirstlane_b32 s4, v1
	s_nop 1
	v_add3_u32 v0, s4, v0, 1
	s_mul_i32 s4, s18, s45
	v_cmp_ne_u32_e32 vcc, s4, v0
	s_and_saveexec_b64 s[4:5], vcc
	v_readlane_b32 s22, v254, 35
	s_xor_b64 s[4:5], exec, s[4:5]
	v_readlane_b32 s23, v254, 36
	s_cbranch_execz .LBB0_1405
	s_nop 3
	v_readlane_b32 vcc_lo, v253, 0
	s_and_b32 vcc_lo, vcc_lo, 15
	s_lshl_b32 vcc_lo, vcc_lo, 7
	s_addk_i32 vcc_lo, 0x1400
	v_mov_b32_e32 v1, vcc_lo
	global_load_dword v0, v1, s[22:23] sc1
	s_waitcnt vmcnt(0)
	v_cmp_le_u32_e32 vcc, s18, v0
	s_cbranch_vccnz .LBB0_1405
.LBB0_1404:
	s_sleep 1
	global_load_dword v0, v1, s[22:23] sc1
	s_waitcnt vmcnt(0)
	v_cmp_gt_u32_e32 vcc, s18, v0
	s_cbranch_vccnz .LBB0_1404
.LBB0_1405:
	s_andn2_saveexec_b64 s[4:5], s[4:5]
	s_cbranch_execz .LBB0_1397
	v_readlane_b32 s6, v254, 35
	v_mov_b32_e32 v0, s18
	v_readlane_b32 s7, v254, 36
	s_nop 4
	v_mov_b32_e32 v1, 0x1400
	global_store_dword v1, v0, s[6:7] sc1
	global_store_dword v1, v0, s[6:7] offset:128 sc1
	global_store_dword v1, v0, s[6:7] offset:256 sc1
	global_store_dword v1, v0, s[6:7] offset:384 sc1
	global_store_dword v1, v0, s[6:7] offset:512 sc1
	global_store_dword v1, v0, s[6:7] offset:640 sc1
	global_store_dword v1, v0, s[6:7] offset:768 sc1
	global_store_dword v1, v0, s[6:7] offset:896 sc1
	global_store_dword v1, v0, s[6:7] offset:1024 sc1
	global_store_dword v1, v0, s[6:7] offset:1152 sc1
	global_store_dword v1, v0, s[6:7] offset:1280 sc1
	global_store_dword v1, v0, s[6:7] offset:1408 sc1
	global_store_dword v1, v0, s[6:7] offset:1536 sc1
	global_store_dword v1, v0, s[6:7] offset:1664 sc1
	global_store_dword v1, v0, s[6:7] offset:1792 sc1
	global_store_dword v1, v0, s[6:7] offset:1920 sc1
	s_branch .LBB0_1397

; __device__ __forceinline__ void grid_barrier(unsigned* bar, unsigned& epoch) {
;     ...
;         const unsigned old = __hip_atomic_fetch_add(bar, 1u, __ATOMIC_RELAXED, __HIP_MEMORY_SCOPE_AGENT);
;         if (old + 1u == epoch * gridDim.x) {
;             __hip_atomic_store(bar + 64, epoch, __ATOMIC_RELAXED, __HIP_MEMORY_SCOPE_AGENT);
;         } else {
;             while (__hip_atomic_load(bar + 64, __ATOMIC_RELAXED, __HIP_MEMORY_SCOPE_AGENT) < epoch) __builtin_amdgcn_s_sleep(1);
;         }
.LBB0_1412:
	s_or_b64 exec, exec, s[6:7]
	s_waitcnt vmcnt(0)
	v_readfirstlane_b32 s4, v1
	s_nop 1
	v_add3_u32 v0, s4, v0, 1
	s_mul_i32 s4, s82, s45
	v_cmp_ne_u32_e32 vcc, s4, v0
	s_and_saveexec_b64 s[4:5], vcc
	v_readlane_b32 s8, v254, 35
	s_xor_b64 s[4:5], exec, s[4:5]
	v_readlane_b32 s9, v254, 36
	s_cbranch_execz .LBB0_1415
	s_nop 3
	v_readlane_b32 vcc_lo, v253, 0
	s_and_b32 vcc_lo, vcc_lo, 15
	s_lshl_b32 vcc_lo, vcc_lo, 7
	s_addk_i32 vcc_lo, 0x1400
	v_mov_b32_e32 v1, vcc_lo
	global_load_dword v0, v1, s[8:9] sc1
	s_waitcnt vmcnt(0)
	v_cmp_le_u32_e32 vcc, s82, v0
	s_cbranch_vccnz .LBB0_1415
.LBB0_1414:
	s_sleep 1
	global_load_dword v0, v1, s[8:9] sc1
	s_waitcnt vmcnt(0)
	v_cmp_gt_u32_e32 vcc, s82, v0
	s_cbranch_vccnz .LBB0_1414

; __device__ __forceinline__ void grid_barrier(unsigned* bar, unsigned& epoch) {
;     ...
;         if (old + 1u == epoch * gridDim.x) {
;             __hip_atomic_store(bar + 64, epoch, __ATOMIC_RELAXED, __HIP_MEMORY_SCOPE_AGENT);
.LBB0_1416:
	v_readlane_b32 s6, v254, 35
	v_mov_b32_e32 v0, s82
	v_readlane_b32 s7, v254, 36
	s_nop 4
	v_mov_b32_e32 v1, 0x1400
	global_store_dword v1, v0, s[6:7] sc1
	global_store_dword v1, v0, s[6:7] offset:128 sc1
	global_store_dword v1, v0, s[6:7] offset:256 sc1
	global_store_dword v1, v0, s[6:7] offset:384 sc1
	global_store_dword v1, v0, s[6:7] offset:512 sc1
	global_store_dword v1, v0, s[6:7] offset:640 sc1
	global_store_dword v1, v0, s[6:7] offset:768 sc1
	global_store_dword v1, v0, s[6:7] offset:896 sc1
	global_store_dword v1, v0, s[6:7] offset:1024 sc1
	global_store_dword v1, v0, s[6:7] offset:1152 sc1
	global_store_dword v1, v0, s[6:7] offset:1280 sc1
	global_store_dword v1, v0, s[6:7] offset:1408 sc1
	global_store_dword v1, v0, s[6:7] offset:1536 sc1
	global_store_dword v1, v0, s[6:7] offset:1664 sc1
	global_store_dword v1, v0, s[6:7] offset:1792 sc1
	global_store_dword v1, v0, s[6:7] offset:1920 sc1
	s_getpc_b64 s[98:99]
